# GEMM K-loop heads aligned to 64 bytes
# baseline (speedup 1.0000x reference)
.LBB0_212:
	v_lshl_add_u64 v[140:141], v[4:5], 0, s[74:75]
	v_mov_b64_e32 v[4:5], 0
	v_lshl_add_u64 v[142:143], v[6:7], 0, s[72:73]
	s_mov_b32 s7, -2
	v_mov_b64_e32 v[6:7], 0
	v_mov_b64_e32 v[8:9], 0
	v_mov_b64_e32 v[10:11], 0
	v_mov_b64_e32 v[20:21], 0
	v_mov_b64_e32 v[22:23], 0
	v_mov_b64_e32 v[24:25], 0
	v_mov_b64_e32 v[26:27], 0
	v_mov_b64_e32 v[36:37], 0
	v_mov_b64_e32 v[38:39], 0
	v_mov_b64_e32 v[40:41], 0
	v_mov_b64_e32 v[42:43], 0
	v_mov_b64_e32 v[52:53], 0
	v_mov_b64_e32 v[54:55], 0
	v_mov_b64_e32 v[56:57], 0
	v_mov_b64_e32 v[58:59], 0
	v_mov_b64_e32 v[12:13], 0
	v_mov_b64_e32 v[14:15], 0
	v_mov_b64_e32 v[16:17], 0
	v_mov_b64_e32 v[18:19], 0
	v_mov_b64_e32 v[28:29], 0
	v_mov_b64_e32 v[30:31], 0
	v_mov_b64_e32 v[32:33], 0
	v_mov_b64_e32 v[34:35], 0
	v_mov_b64_e32 v[44:45], 0
	v_mov_b64_e32 v[46:47], 0
	v_mov_b64_e32 v[48:49], 0
	v_mov_b64_e32 v[50:51], 0
	v_mov_b64_e32 v[60:61], 0
	v_mov_b64_e32 v[62:63], 0
	v_mov_b64_e32 v[64:65], 0
	v_mov_b64_e32 v[66:67], 0
	v_mov_b64_e32 v[68:69], 0
	v_mov_b64_e32 v[70:71], 0
	v_mov_b64_e32 v[72:73], 0
	v_mov_b64_e32 v[74:75], 0
	v_mov_b64_e32 v[84:85], 0
	v_mov_b64_e32 v[86:87], 0
	v_mov_b64_e32 v[88:89], 0
	v_mov_b64_e32 v[90:91], 0
	v_mov_b64_e32 v[100:101], 0
	v_mov_b64_e32 v[102:103], 0
	v_mov_b64_e32 v[104:105], 0
	v_mov_b64_e32 v[106:107], 0
	v_mov_b64_e32 v[116:117], 0
	v_mov_b64_e32 v[118:119], 0
	v_mov_b64_e32 v[120:121], 0
	v_mov_b64_e32 v[122:123], 0
	v_mov_b64_e32 v[76:77], 0
	v_mov_b64_e32 v[78:79], 0
	v_mov_b64_e32 v[80:81], 0
	v_mov_b64_e32 v[82:83], 0
	v_mov_b64_e32 v[92:93], 0
	v_mov_b64_e32 v[94:95], 0
	v_mov_b64_e32 v[96:97], 0
	v_mov_b64_e32 v[98:99], 0
	v_mov_b64_e32 v[108:109], 0
	v_mov_b64_e32 v[110:111], 0
	v_mov_b64_e32 v[112:113], 0
	v_mov_b64_e32 v[114:115], 0
	v_mov_b64_e32 v[124:125], 0
	v_mov_b64_e32 v[126:127], 0
	v_mov_b64_e32 v[128:129], 0
	v_mov_b64_e32 v[130:131], 0
	.p2alignl 6, 3212836864

.LBB0_369:
	s_ashr_i32 s35, s34, 31
	s_lshl_b64 s[6:7], s[34:35], 19
	s_add_u32 s38, s45, s6
	s_addc_u32 s39, s48, s7
	s_and_b64 s[6:7], s[4:5], exec
	s_cselect_b32 s1, s39, s9
	s_cselect_b32 s3, s38, s8
	s_ashr_i32 s41, s40, 31
	s_lshl_b64 s[6:7], s[40:41], 19
	s_add_u32 s18, s49, s6
	s_addc_u32 s19, s54, s7
	s_and_b64 s[6:7], s[4:5], exec
	s_cselect_b32 s12, s19, s11
	s_cselect_b32 s13, s18, s10
	s_add_u32 s6, s8, 0x40080
	s_addc_u32 s7, s9, 0
	s_add_u32 s14, s10, 0x100
	v_mov_b64_e32 v[4:5], 0
	s_addc_u32 s15, s11, 0
	s_mov_b32 s21, -2
	v_mov_b64_e32 v[6:7], 0
	v_mov_b64_e32 v[40:41], 0
	v_mov_b64_e32 v[42:43], 0
	v_mov_b64_e32 v[8:9], 0
	v_mov_b64_e32 v[10:11], 0
	v_mov_b64_e32 v[44:45], 0
	v_mov_b64_e32 v[46:47], 0
	v_mov_b64_e32 v[12:13], 0
	v_mov_b64_e32 v[14:15], 0
	v_mov_b64_e32 v[48:49], 0
	v_mov_b64_e32 v[50:51], 0
	v_mov_b64_e32 v[16:17], 0
	v_mov_b64_e32 v[18:19], 0
	v_mov_b64_e32 v[52:53], 0
	v_mov_b64_e32 v[54:55], 0
	v_mov_b64_e32 v[36:37], 0
	v_mov_b64_e32 v[38:39], 0
	v_mov_b64_e32 v[32:33], 0
	v_mov_b64_e32 v[34:35], 0
	v_mov_b64_e32 v[20:21], 0
	v_mov_b64_e32 v[22:23], 0
	v_mov_b64_e32 v[56:57], 0
	v_mov_b64_e32 v[58:59], 0
	v_mov_b64_e32 v[24:25], 0
	v_mov_b64_e32 v[26:27], 0
	v_mov_b64_e32 v[60:61], 0
	v_mov_b64_e32 v[62:63], 0
	v_mov_b64_e32 v[28:29], 0
	v_mov_b64_e32 v[30:31], 0
	v_mov_b64_e32 v[64:65], 0
	v_mov_b64_e32 v[66:67], 0
	s_waitcnt vmcnt(4)
	v_mov_b64_e32 v[68:69], 0
	v_mov_b64_e32 v[70:71], 0
	v_mov_b64_e32 v[116:117], 0
	v_mov_b64_e32 v[118:119], 0
	v_mov_b64_e32 v[72:73], 0
	v_mov_b64_e32 v[74:75], 0
	v_mov_b64_e32 v[120:121], 0
	v_mov_b64_e32 v[122:123], 0
	v_mov_b64_e32 v[76:77], 0
	v_mov_b64_e32 v[78:79], 0
	v_mov_b64_e32 v[124:125], 0
	v_mov_b64_e32 v[126:127], 0
	v_mov_b64_e32 v[80:81], 0
	v_mov_b64_e32 v[82:83], 0
	v_mov_b64_e32 v[128:129], 0
	v_mov_b64_e32 v[130:131], 0
	v_mov_b64_e32 v[112:113], 0
	v_mov_b64_e32 v[114:115], 0
	v_mov_b64_e32 v[108:109], 0
	v_mov_b64_e32 v[110:111], 0
	v_mov_b64_e32 v[84:85], 0
	v_mov_b64_e32 v[86:87], 0
	v_mov_b64_e32 v[132:133], 0
	v_mov_b64_e32 v[134:135], 0
	v_mov_b64_e32 v[88:89], 0
	v_mov_b64_e32 v[90:91], 0
	v_mov_b64_e32 v[136:137], 0
	v_mov_b64_e32 v[138:139], 0
	v_mov_b64_e32 v[92:93], 0
	v_mov_b64_e32 v[94:95], 0
	v_mov_b64_e32 v[140:141], 0
	v_mov_b64_e32 v[142:143], 0
	.p2alignl 6, 3212836864

.LBB0_769:
	s_add_u32 s6, s42, 0x80
	s_addc_u32 s7, s43, 0
	s_add_u32 s52, s52, 0x100
	v_mov_b64_e32 v[4:5], 0
	s_addc_u32 s53, s53, 0
	s_mov_b32 s42, 0
	v_mov_b64_e32 v[6:7], 0
	v_mov_b64_e32 v[8:9], 0
	v_mov_b64_e32 v[10:11], 0
	v_mov_b64_e32 v[20:21], 0
	v_mov_b64_e32 v[22:23], 0
	v_mov_b64_e32 v[24:25], 0
	v_mov_b64_e32 v[26:27], 0
	v_mov_b64_e32 v[36:37], 0
	v_mov_b64_e32 v[38:39], 0
	v_mov_b64_e32 v[40:41], 0
	v_mov_b64_e32 v[42:43], 0
	v_mov_b64_e32 v[52:53], 0
	v_mov_b64_e32 v[54:55], 0
	v_mov_b64_e32 v[56:57], 0
	v_mov_b64_e32 v[58:59], 0
	v_mov_b64_e32 v[12:13], 0
	v_mov_b64_e32 v[14:15], 0
	v_mov_b64_e32 v[16:17], 0
	v_mov_b64_e32 v[18:19], 0
	v_mov_b64_e32 v[28:29], 0
	v_mov_b64_e32 v[30:31], 0
	v_mov_b64_e32 v[32:33], 0
	v_mov_b64_e32 v[34:35], 0
	v_mov_b64_e32 v[44:45], 0
	v_mov_b64_e32 v[46:47], 0
	v_mov_b64_e32 v[48:49], 0
	v_mov_b64_e32 v[50:51], 0
	v_mov_b64_e32 v[60:61], 0
	v_mov_b64_e32 v[62:63], 0
	v_mov_b64_e32 v[64:65], 0
	v_mov_b64_e32 v[66:67], 0
	s_waitcnt vmcnt(4)
	v_mov_b64_e32 v[68:69], 0
	v_mov_b64_e32 v[70:71], 0
	v_mov_b64_e32 v[72:73], 0
	v_mov_b64_e32 v[74:75], 0
	v_mov_b64_e32 v[84:85], 0
	v_mov_b64_e32 v[86:87], 0
	v_mov_b64_e32 v[88:89], 0
	v_mov_b64_e32 v[90:91], 0
	v_mov_b64_e32 v[100:101], 0
	v_mov_b64_e32 v[102:103], 0
	v_mov_b64_e32 v[104:105], 0
	v_mov_b64_e32 v[106:107], 0
	v_mov_b64_e32 v[116:117], 0
	v_mov_b64_e32 v[118:119], 0
	v_mov_b64_e32 v[120:121], 0
	v_mov_b64_e32 v[122:123], 0
	v_mov_b64_e32 v[76:77], 0
	v_mov_b64_e32 v[78:79], 0
	v_mov_b64_e32 v[80:81], 0
	v_mov_b64_e32 v[82:83], 0
	v_mov_b64_e32 v[92:93], 0
	v_mov_b64_e32 v[94:95], 0
	v_mov_b64_e32 v[96:97], 0
	v_mov_b64_e32 v[98:99], 0
	v_mov_b64_e32 v[108:109], 0
	v_mov_b64_e32 v[110:111], 0
	v_mov_b64_e32 v[112:113], 0
	v_mov_b64_e32 v[114:115], 0
	v_mov_b64_e32 v[124:125], 0
	v_mov_b64_e32 v[126:127], 0
	v_mov_b64_e32 v[128:129], 0
	v_mov_b64_e32 v[130:131], 0
	.p2alignl 6, 3212836864

.LBB0_938:
	s_add_u32 s38, s38, 0x80
	s_addc_u32 s39, s39, 0
	s_add_u32 s31, s40, 0x100
	v_mov_b64_e32 v[4:5], 0
	s_addc_u32 s35, s41, 0
	s_mov_b32 s40, 0
	v_mov_b64_e32 v[6:7], 0
	v_mov_b64_e32 v[8:9], 0
	v_mov_b64_e32 v[10:11], 0
	v_mov_b64_e32 v[20:21], 0
	v_mov_b64_e32 v[22:23], 0
	v_mov_b64_e32 v[24:25], 0
	v_mov_b64_e32 v[26:27], 0
	v_mov_b64_e32 v[36:37], 0
	v_mov_b64_e32 v[38:39], 0
	v_mov_b64_e32 v[40:41], 0
	v_mov_b64_e32 v[42:43], 0
	v_mov_b64_e32 v[52:53], 0
	v_mov_b64_e32 v[54:55], 0
	v_mov_b64_e32 v[56:57], 0
	v_mov_b64_e32 v[58:59], 0
	v_mov_b64_e32 v[12:13], 0
	v_mov_b64_e32 v[14:15], 0
	v_mov_b64_e32 v[16:17], 0
	v_mov_b64_e32 v[18:19], 0
	v_mov_b64_e32 v[28:29], 0
	v_mov_b64_e32 v[30:31], 0
	v_mov_b64_e32 v[32:33], 0
	v_mov_b64_e32 v[34:35], 0
	v_mov_b64_e32 v[44:45], 0
	v_mov_b64_e32 v[46:47], 0
	v_mov_b64_e32 v[48:49], 0
	v_mov_b64_e32 v[50:51], 0
	v_mov_b64_e32 v[60:61], 0
	v_mov_b64_e32 v[62:63], 0
	v_mov_b64_e32 v[64:65], 0
	v_mov_b64_e32 v[66:67], 0
	v_mov_b64_e32 v[68:69], 0
	v_mov_b64_e32 v[70:71], 0
	v_mov_b64_e32 v[72:73], 0
	v_mov_b64_e32 v[74:75], 0
	v_mov_b64_e32 v[84:85], 0
	v_mov_b64_e32 v[86:87], 0
	v_mov_b64_e32 v[88:89], 0
	v_mov_b64_e32 v[90:91], 0
	v_mov_b64_e32 v[100:101], 0
	v_mov_b64_e32 v[102:103], 0
	v_mov_b64_e32 v[104:105], 0
	v_mov_b64_e32 v[106:107], 0
	v_mov_b64_e32 v[116:117], 0
	v_mov_b64_e32 v[118:119], 0
	v_mov_b64_e32 v[120:121], 0
	v_mov_b64_e32 v[122:123], 0
	v_mov_b64_e32 v[76:77], 0
	v_mov_b64_e32 v[78:79], 0
	v_mov_b64_e32 v[80:81], 0
	v_mov_b64_e32 v[82:83], 0
	v_mov_b64_e32 v[92:93], 0
	v_mov_b64_e32 v[94:95], 0
	v_mov_b64_e32 v[96:97], 0
	v_mov_b64_e32 v[98:99], 0
	v_mov_b64_e32 v[108:109], 0
	v_mov_b64_e32 v[110:111], 0
	v_mov_b64_e32 v[112:113], 0
	v_mov_b64_e32 v[114:115], 0
	v_mov_b64_e32 v[124:125], 0
	v_mov_b64_e32 v[126:127], 0
	v_mov_b64_e32 v[128:129], 0
	v_mov_b64_e32 v[130:131], 0
	.p2alignl 6, 3212836864
